# v70 + dn_pre: diagonal-block inverse multiply reads batched (one LDS round trip per block row)
# baseline (speedup 1.0000x reference)
.LBB0_420:
	s_nop 7
	ds_write2_b32 v17, v4, v8 offset1:16
	ds_write2_b32 v17, v5, v9 offset0:132 offset1:148
	ds_write2_b32 v18, v6, v10 offset0:8 offset1:24
	ds_write2_b32 v18, v7, v11 offset0:140 offset1:156
	s_waitcnt lgkmcnt(0)
	v_lshl_or_b32 v19, s21, 10, v14
	ds_read2st64_b32 v[44:45], v19 offset0:200 offset1:201
	ds_read2st64_b32 v[46:47], v19 offset0:202 offset1:203
	v_or_b32_e32 v4, s36, v1
	v_mad_u64_u32 v[22:23], s[36:37], v4, s33, v[12:13]
	ds_read2_b32 v[48:49], v22 offset1:16
	v_add_u32_e32 v20, 0x800, v22
	ds_read2_b32 v[50:51], v20 offset0:16 offset1:32
	v_add_u32_e32 v19, 0x1000, v22
	ds_read2_b32 v[52:53], v19 offset0:32 offset1:48
	v_add_u32_e32 v19, 0x1800, v22
	ds_read2_b32 v[54:55], v19 offset0:48 offset1:64
	s_add_i32 s21, s21, 1
	s_add_i32 s20, s20, 4
	v_add_u32_e32 v16, 64, v16
	s_waitcnt lgkmcnt(3)
	v_mfma_f32_16x16x4_f32 v[4:7], v44, v48, 0
	s_cmp_eq_u32 s21, 4
	v_mfma_f32_16x16x4_f32 v[8:11], v44, v49, 0
	s_waitcnt lgkmcnt(2)
	v_mfma_f32_16x16x4_f32 v[4:7], v45, v50, v[4:7]
	v_mfma_f32_16x16x4_f32 v[8:11], v45, v51, v[8:11]
	s_waitcnt lgkmcnt(1)
	v_mfma_f32_16x16x4_f32 v[4:7], v46, v52, v[4:7]
	v_mfma_f32_16x16x4_f32 v[8:11], v46, v53, v[8:11]
	s_waitcnt lgkmcnt(0)
	v_mfma_f32_16x16x4_f32 v[4:7], v47, v54, v[4:7]
	v_mfma_f32_16x16x4_f32 v[8:11], v47, v55, v[8:11]
	s_nop 9
	ds_write2_b32 v17, v4, v8 offset1:16
	ds_write2_b32 v17, v5, v9 offset0:132 offset1:148
	ds_write2_b32 v18, v6, v10 offset0:8 offset1:24
	ds_write2_b32 v18, v7, v11 offset0:140 offset1:156
	s_waitcnt lgkmcnt(0)
	s_cbranch_scc1 .LBB0_396
